# v16 + grid barrier arrival/release rewritten: last WG of each XCD bumps TOP (no fetch result needed), everybody polls TOP >= (j+1)*nx; no TOPGEN / per-XCD generation hops, no divisions
# speedup vs baseline: 1.0506x; 1.0034x over previous
.LBB0_106:
	s_waitcnt lgkmcnt(0)
	v_readlane_b32 s98, v237, 3
	v_readlane_b32 s99, v237, 4
	v_readlane_b32 s100, v237, 33
	s_lshl_b32 s100, s100, 8
	s_add_u32 s100, s98, s100
	s_addc_u32 s101, s99, 0
	v_mov_b32_e32 v1, 1
	v_mov_b32_e32 v3, 0x1400
	global_atomic_add v3, v3, v1, s[100:101] sc0
	v_mul_u32_u24_e32 v4, 1, v2
	v_mul_u32_u24_e32 v5, 1, v0
	s_add_u32 s98, s98, 0x3400
	s_addc_u32 s99, s99, 0
	v_mov_b32_e32 v1, 0
	s_waitcnt vmcnt(0)
	v_add_u32_e32 v3, 1, v3
	v_cmp_ne_u32_e32 vcc, v3, v4
	s_cbranch_vccnz .Lmy_xb0_poll
	buffer_wbl2 sc1
	s_waitcnt vmcnt(0)
	v_mov_b32_e32 v3, 1
	global_atomic_add v1, v3, s[98:99]
.Lmy_xb0_poll:
	s_mov_b32 s100, 0
.Lmy_xb0_loop:
	global_load_dword v3, v1, s[98:99] sc1
	s_waitcnt vmcnt(0)
	v_cmp_ge_u32_e32 vcc, v3, v5
	s_cbranch_vccnz .Lmy_xb0_done
	s_sleep 1
	s_add_u32 s100, s100, 1
	s_cmp_lt_u32 s100, 0x400000
	s_cbranch_scc1 .Lmy_xb0_loop
.Lmy_xb0_done:
	buffer_inv sc1
	s_waitcnt vmcnt(0)

.LBB0_192:
	s_waitcnt lgkmcnt(0)
	v_readlane_b32 s98, v237, 3
	v_readlane_b32 s99, v237, 4
	v_readlane_b32 s100, v237, 33
	s_lshl_b32 s100, s100, 8
	s_add_u32 s100, s98, s100
	s_addc_u32 s101, s99, 0
	v_mov_b32_e32 v1, 1
	v_mov_b32_e32 v3, 0x1400
	global_atomic_add v3, v3, v1, s[100:101] sc0
	v_mul_u32_u24_e32 v4, 2, v2
	v_mul_u32_u24_e32 v5, 2, v0
	s_add_u32 s98, s98, 0x3400
	s_addc_u32 s99, s99, 0
	v_mov_b32_e32 v1, 0
	s_waitcnt vmcnt(0)
	v_add_u32_e32 v3, 1, v3
	v_cmp_ne_u32_e32 vcc, v3, v4
	s_cbranch_vccnz .Lmy_xb1_poll
	buffer_wbl2 sc1
	s_waitcnt vmcnt(0)
	v_mov_b32_e32 v3, 1
	global_atomic_add v1, v3, s[98:99]

.LBB0_267:
	s_waitcnt lgkmcnt(0)
	v_readlane_b32 s98, v237, 3
	v_readlane_b32 s99, v237, 4
	v_readlane_b32 s100, v237, 33
	s_lshl_b32 s100, s100, 8
	s_add_u32 s100, s98, s100
	s_addc_u32 s101, s99, 0
	v_mov_b32_e32 v1, 1
	v_mov_b32_e32 v3, 0x1400
	global_atomic_add v3, v3, v1, s[100:101] sc0
	v_mul_u32_u24_e32 v4, 3, v2
	v_mul_u32_u24_e32 v5, 3, v0
	s_add_u32 s98, s98, 0x3400
	s_addc_u32 s99, s99, 0
	v_mov_b32_e32 v1, 0
	s_waitcnt vmcnt(0)
	v_add_u32_e32 v3, 1, v3
	v_cmp_ne_u32_e32 vcc, v3, v4
	s_cbranch_vccnz .Lmy_xb2_poll
	buffer_wbl2 sc1
	s_waitcnt vmcnt(0)
	v_mov_b32_e32 v3, 1
	global_atomic_add v1, v3, s[98:99]

.LBB0_351:
	s_waitcnt lgkmcnt(0)
	v_readlane_b32 s98, v237, 3
	v_readlane_b32 s99, v237, 4
	v_readlane_b32 s100, v237, 33
	s_lshl_b32 s100, s100, 8
	s_add_u32 s100, s98, s100
	s_addc_u32 s101, s99, 0
	v_mov_b32_e32 v1, 1
	v_mov_b32_e32 v3, 0x1400
	global_atomic_add v3, v3, v1, s[100:101] sc0
	v_mul_u32_u24_e32 v4, 4, v2
	v_mul_u32_u24_e32 v5, 4, v0
	s_add_u32 s98, s98, 0x3400
	s_addc_u32 s99, s99, 0
	v_mov_b32_e32 v1, 0
	s_waitcnt vmcnt(0)
	v_add_u32_e32 v3, 1, v3
	v_cmp_ne_u32_e32 vcc, v3, v4
	s_cbranch_vccnz .Lmy_xb3_poll
	buffer_wbl2 sc1
	s_waitcnt vmcnt(0)
	v_mov_b32_e32 v3, 1
	global_atomic_add v1, v3, s[98:99]

.LBB0_430:
	s_waitcnt lgkmcnt(0)
	v_readlane_b32 s98, v237, 3
	v_readlane_b32 s99, v237, 4
	v_readlane_b32 s100, v237, 33
	s_lshl_b32 s100, s100, 8
	s_add_u32 s100, s98, s100
	s_addc_u32 s101, s99, 0
	v_mov_b32_e32 v1, 1
	v_mov_b32_e32 v3, 0x1400
	global_atomic_add v3, v3, v1, s[100:101] sc0
	v_mul_u32_u24_e32 v4, 5, v2
	v_mul_u32_u24_e32 v5, 5, v0
	s_add_u32 s98, s98, 0x3400
	s_addc_u32 s99, s99, 0
	v_mov_b32_e32 v1, 0
	s_waitcnt vmcnt(0)
	v_add_u32_e32 v3, 1, v3
	v_cmp_ne_u32_e32 vcc, v3, v4
	s_cbranch_vccnz .Lmy_xb4_poll
	buffer_wbl2 sc1
	s_waitcnt vmcnt(0)
	v_mov_b32_e32 v3, 1
	global_atomic_add v1, v3, s[98:99]

.LBB0_509:
	s_waitcnt lgkmcnt(0)
	v_readlane_b32 s98, v237, 3
	v_readlane_b32 s99, v237, 4
	v_readlane_b32 s100, v237, 33
	s_lshl_b32 s100, s100, 8
	s_add_u32 s100, s98, s100
	s_addc_u32 s101, s99, 0
	v_mov_b32_e32 v1, 1
	v_mov_b32_e32 v3, 0x1400
	global_atomic_add v3, v3, v1, s[100:101] sc0
	v_mul_u32_u24_e32 v4, 6, v2
	v_mul_u32_u24_e32 v5, 6, v0
	s_add_u32 s98, s98, 0x3400
	s_addc_u32 s99, s99, 0
	v_mov_b32_e32 v1, 0
	s_waitcnt vmcnt(0)
	v_add_u32_e32 v3, 1, v3
	v_cmp_ne_u32_e32 vcc, v3, v4
	s_cbranch_vccnz .Lmy_xb5_poll
	buffer_wbl2 sc1
	s_waitcnt vmcnt(0)
	v_mov_b32_e32 v3, 1
	global_atomic_add v1, v3, s[98:99]

.LBB0_610:
	s_waitcnt lgkmcnt(0)
	v_readlane_b32 s98, v237, 3
	v_readlane_b32 s99, v237, 4
	v_readlane_b32 s100, v237, 33
	s_lshl_b32 s100, s100, 8
	s_add_u32 s100, s98, s100
	s_addc_u32 s101, s99, 0
	v_mov_b32_e32 v1, 1
	v_mov_b32_e32 v3, 0x1400
	global_atomic_add v3, v3, v1, s[100:101] sc0
	v_mul_u32_u24_e32 v4, 7, v2
	v_mul_u32_u24_e32 v5, 7, v0
	s_add_u32 s98, s98, 0x3400
	s_addc_u32 s99, s99, 0
	v_mov_b32_e32 v1, 0
	s_waitcnt vmcnt(0)
	v_add_u32_e32 v3, 1, v3
	v_cmp_ne_u32_e32 vcc, v3, v4
	s_cbranch_vccnz .Lmy_xb6_poll
	buffer_wbl2 sc1
	s_waitcnt vmcnt(0)
	v_mov_b32_e32 v3, 1
	global_atomic_add v1, v3, s[98:99]

.LBB0_750:
	s_waitcnt lgkmcnt(0)
	v_readlane_b32 s98, v237, 3
	v_readlane_b32 s99, v237, 4
	v_readlane_b32 s100, v237, 33
	s_lshl_b32 s100, s100, 8
	s_add_u32 s100, s98, s100
	s_addc_u32 s101, s99, 0
	v_mov_b32_e32 v1, 1
	v_mov_b32_e32 v3, 0x1400
	global_atomic_add v3, v3, v1, s[100:101] sc0
	v_mul_u32_u24_e32 v4, 8, v2
	v_mul_u32_u24_e32 v5, 8, v0
	s_add_u32 s98, s98, 0x3400
	s_addc_u32 s99, s99, 0
	v_mov_b32_e32 v1, 0
	s_waitcnt vmcnt(0)
	v_add_u32_e32 v3, 1, v3
	v_cmp_ne_u32_e32 vcc, v3, v4
	s_cbranch_vccnz .Lmy_xb7_poll
	buffer_wbl2 sc1
	s_waitcnt vmcnt(0)
	v_mov_b32_e32 v3, 1
	global_atomic_add v1, v3, s[98:99]

.LBB0_889:
	s_waitcnt lgkmcnt(0)
	v_readlane_b32 s98, v237, 3
	v_readlane_b32 s99, v237, 4
	v_readlane_b32 s100, v237, 33
	s_lshl_b32 s100, s100, 8
	s_add_u32 s100, s98, s100
	s_addc_u32 s101, s99, 0
	v_mov_b32_e32 v1, 1
	v_mov_b32_e32 v3, 0x1400
	global_atomic_add v3, v3, v1, s[100:101] sc0
	v_mul_u32_u24_e32 v4, 9, v2
	v_mul_u32_u24_e32 v5, 9, v0
	s_add_u32 s98, s98, 0x3400
	s_addc_u32 s99, s99, 0
	v_mov_b32_e32 v1, 0
	s_waitcnt vmcnt(0)
	v_add_u32_e32 v3, 1, v3
	v_cmp_ne_u32_e32 vcc, v3, v4
	s_cbranch_vccnz .Lmy_xb8_poll
	buffer_wbl2 sc1
	s_waitcnt vmcnt(0)
	v_mov_b32_e32 v3, 1
	global_atomic_add v1, v3, s[98:99]

.LBB0_944:
	s_waitcnt lgkmcnt(0)
	v_readlane_b32 s98, v237, 3
	v_readlane_b32 s99, v237, 4
	v_readlane_b32 s100, v237, 33
	s_lshl_b32 s100, s100, 8
	s_add_u32 s100, s98, s100
	s_addc_u32 s101, s99, 0
	v_mov_b32_e32 v1, 1
	v_mov_b32_e32 v3, 0x1400
	global_atomic_add v3, v3, v1, s[100:101] sc0
	v_mul_u32_u24_e32 v4, 10, v2
	v_mul_u32_u24_e32 v5, 10, v0
	s_add_u32 s98, s98, 0x3400
	s_addc_u32 s99, s99, 0
	v_mov_b32_e32 v1, 0
	s_waitcnt vmcnt(0)
	v_add_u32_e32 v3, 1, v3
	v_cmp_ne_u32_e32 vcc, v3, v4
	s_cbranch_vccnz .Lmy_xb9_poll
	buffer_wbl2 sc1
	s_waitcnt vmcnt(0)
	v_mov_b32_e32 v3, 1
	global_atomic_add v1, v3, s[98:99]

.LBB0_1031:
	s_waitcnt lgkmcnt(0)
	v_readlane_b32 s98, v237, 3
	v_readlane_b32 s99, v237, 4
	v_readlane_b32 s100, v237, 33
	s_lshl_b32 s100, s100, 8
	s_add_u32 s100, s98, s100
	s_addc_u32 s101, s99, 0
	v_mov_b32_e32 v1, 1
	v_mov_b32_e32 v3, 0x1400
	global_atomic_add v3, v3, v1, s[100:101] sc0
	v_mul_u32_u24_e32 v4, 11, v2
	v_mul_u32_u24_e32 v5, 11, v0
	s_add_u32 s98, s98, 0x3400
	s_addc_u32 s99, s99, 0
	v_mov_b32_e32 v1, 0
	s_waitcnt vmcnt(0)
	v_add_u32_e32 v3, 1, v3
	v_cmp_ne_u32_e32 vcc, v3, v4
	s_cbranch_vccnz .Lmy_xb10_poll
	buffer_wbl2 sc1
	s_waitcnt vmcnt(0)
	v_mov_b32_e32 v3, 1
	global_atomic_add v1, v3, s[98:99]

.LBB0_1094:
	s_waitcnt lgkmcnt(0)
	v_readlane_b32 s98, v237, 3
	v_readlane_b32 s99, v237, 4
	v_readlane_b32 s100, v237, 33
	s_lshl_b32 s100, s100, 8
	s_add_u32 s100, s98, s100
	s_addc_u32 s101, s99, 0
	v_mov_b32_e32 v1, 1
	v_mov_b32_e32 v3, 0x1400
	global_atomic_add v3, v3, v1, s[100:101] sc0
	v_mul_u32_u24_e32 v4, 12, v2
	v_mul_u32_u24_e32 v5, 12, v0
	s_add_u32 s98, s98, 0x3400
	s_addc_u32 s99, s99, 0
	v_mov_b32_e32 v1, 0
	s_waitcnt vmcnt(0)
	v_add_u32_e32 v3, 1, v3
	v_cmp_ne_u32_e32 vcc, v3, v4
	s_cbranch_vccnz .Lmy_xb11_poll
	buffer_wbl2 sc1
	s_waitcnt vmcnt(0)
	v_mov_b32_e32 v3, 1
	global_atomic_add v1, v3, s[98:99]

.LBB0_1412:
	s_waitcnt lgkmcnt(0)
	v_readlane_b32 s98, v237, 3
	v_readlane_b32 s99, v237, 4
	v_readlane_b32 s100, v237, 33
	s_lshl_b32 s100, s100, 8
	s_add_u32 s100, s98, s100
	s_addc_u32 s101, s99, 0
	v_mov_b32_e32 v1, 1
	v_mov_b32_e32 v3, 0x1400
	global_atomic_add v3, v3, v1, s[100:101] sc0
	v_mul_u32_u24_e32 v4, 13, v2
	v_mul_u32_u24_e32 v5, 13, v0
	s_add_u32 s98, s98, 0x3400
	s_addc_u32 s99, s99, 0
	v_mov_b32_e32 v1, 0
	s_waitcnt vmcnt(0)
	v_add_u32_e32 v3, 1, v3
	v_cmp_ne_u32_e32 vcc, v3, v4
	s_cbranch_vccnz .Lmy_xb12_poll
	buffer_wbl2 sc1
	s_waitcnt vmcnt(0)
	v_mov_b32_e32 v3, 1
	global_atomic_add v1, v3, s[98:99]

.LBB0_1493:
	s_waitcnt lgkmcnt(0)
	v_readlane_b32 s98, v237, 3
	v_readlane_b32 s99, v237, 4
	v_readlane_b32 s100, v237, 33
	s_lshl_b32 s100, s100, 8
	s_add_u32 s100, s98, s100
	s_addc_u32 s101, s99, 0
	v_mov_b32_e32 v1, 1
	v_mov_b32_e32 v3, 0x1400
	global_atomic_add v3, v3, v1, s[100:101] sc0
	v_mul_u32_u24_e32 v4, 14, v2
	v_mul_u32_u24_e32 v5, 14, v0
	s_add_u32 s98, s98, 0x3400
	s_addc_u32 s99, s99, 0
	v_mov_b32_e32 v1, 0
	s_waitcnt vmcnt(0)
	v_add_u32_e32 v3, 1, v3
	v_cmp_ne_u32_e32 vcc, v3, v4
	s_cbranch_vccnz .Lmy_xb13_poll
	buffer_wbl2 sc1
	s_waitcnt vmcnt(0)
	v_mov_b32_e32 v3, 1
	global_atomic_add v1, v3, s[98:99]

.LBB0_1554:
	s_waitcnt lgkmcnt(0)
	v_readlane_b32 s98, v237, 3
	v_readlane_b32 s99, v237, 4
	v_readlane_b32 s100, v237, 33
	s_lshl_b32 s100, s100, 8
	s_add_u32 s100, s98, s100
	s_addc_u32 s101, s99, 0
	v_mov_b32_e32 v1, 1
	v_mov_b32_e32 v3, 0x1400
	global_atomic_add v3, v3, v1, s[100:101] sc0
	v_mul_u32_u24_e32 v4, 15, v2
	v_mul_u32_u24_e32 v5, 15, v0
	s_add_u32 s98, s98, 0x3400
	s_addc_u32 s99, s99, 0
	v_mov_b32_e32 v1, 0
	s_waitcnt vmcnt(0)
	v_add_u32_e32 v3, 1, v3
	v_cmp_ne_u32_e32 vcc, v3, v4
	s_cbranch_vccnz .Lmy_xb14_poll
	buffer_wbl2 sc1
	s_waitcnt vmcnt(0)
	v_mov_b32_e32 v3, 1
	global_atomic_add v1, v3, s[98:99]

.LBB0_1633:
	s_waitcnt lgkmcnt(0)
	v_readlane_b32 s98, v237, 3
	v_readlane_b32 s99, v237, 4
	v_readlane_b32 s100, v237, 33
	s_lshl_b32 s100, s100, 8
	s_add_u32 s100, s98, s100
	s_addc_u32 s101, s99, 0
	v_mov_b32_e32 v1, 1
	v_mov_b32_e32 v3, 0x1400
	global_atomic_add v3, v3, v1, s[100:101] sc0
	v_mul_u32_u24_e32 v4, 16, v2
	v_mul_u32_u24_e32 v5, 16, v0
	s_add_u32 s98, s98, 0x3400
	s_addc_u32 s99, s99, 0
	v_mov_b32_e32 v1, 0
	s_waitcnt vmcnt(0)
	v_add_u32_e32 v3, 1, v3
	v_cmp_ne_u32_e32 vcc, v3, v4
	s_cbranch_vccnz .Lmy_xb15_poll
	buffer_wbl2 sc1
	s_waitcnt vmcnt(0)
	v_mov_b32_e32 v3, 1
	global_atomic_add v1, v3, s[98:99]

.LBB0_1734:
	s_waitcnt lgkmcnt(0)
	v_readlane_b32 s98, v237, 3
	v_readlane_b32 s99, v237, 4
	v_readlane_b32 s100, v237, 33
	s_lshl_b32 s100, s100, 8
	s_add_u32 s100, s98, s100
	s_addc_u32 s101, s99, 0
	v_mov_b32_e32 v1, 1
	v_mov_b32_e32 v3, 0x1400
	global_atomic_add v3, v3, v1, s[100:101] sc0
	v_mul_u32_u24_e32 v4, 17, v2
	v_mul_u32_u24_e32 v5, 17, v0
	s_add_u32 s98, s98, 0x3400
	s_addc_u32 s99, s99, 0
	v_mov_b32_e32 v1, 0
	s_waitcnt vmcnt(0)
	v_add_u32_e32 v3, 1, v3
	v_cmp_ne_u32_e32 vcc, v3, v4
	s_cbranch_vccnz .Lmy_xb16_poll
	buffer_wbl2 sc1
	s_waitcnt vmcnt(0)
	v_mov_b32_e32 v3, 1
	global_atomic_add v1, v3, s[98:99]

.LBB0_1874:
	s_waitcnt lgkmcnt(0)
	v_readlane_b32 s98, v237, 3
	v_readlane_b32 s99, v237, 4
	v_readlane_b32 s100, v237, 33
	s_lshl_b32 s100, s100, 8
	s_add_u32 s100, s98, s100
	s_addc_u32 s101, s99, 0
	v_mov_b32_e32 v1, 1
	v_mov_b32_e32 v3, 0x1400
	global_atomic_add v3, v3, v1, s[100:101] sc0
	v_mul_u32_u24_e32 v4, 18, v2
	v_mul_u32_u24_e32 v5, 18, v0
	s_add_u32 s98, s98, 0x3400
	s_addc_u32 s99, s99, 0
	v_mov_b32_e32 v1, 0
	s_waitcnt vmcnt(0)
	v_add_u32_e32 v3, 1, v3
	v_cmp_ne_u32_e32 vcc, v3, v4
	s_cbranch_vccnz .Lmy_xb17_poll
	buffer_wbl2 sc1
	s_waitcnt vmcnt(0)
	v_mov_b32_e32 v3, 1
	global_atomic_add v1, v3, s[98:99]

.LBB0_2013:
	s_waitcnt lgkmcnt(0)
	v_readlane_b32 s98, v237, 3
	v_readlane_b32 s99, v237, 4
	v_readlane_b32 s100, v237, 33
	s_lshl_b32 s100, s100, 8
	s_add_u32 s100, s98, s100
	s_addc_u32 s101, s99, 0
	v_mov_b32_e32 v1, 1
	v_mov_b32_e32 v3, 0x1400
	global_atomic_add v3, v3, v1, s[100:101] sc0
	v_mul_u32_u24_e32 v4, 19, v2
	v_mul_u32_u24_e32 v5, 19, v0
	s_add_u32 s98, s98, 0x3400
	s_addc_u32 s99, s99, 0
	v_mov_b32_e32 v1, 0
	s_waitcnt vmcnt(0)
	v_add_u32_e32 v3, 1, v3
	v_cmp_ne_u32_e32 vcc, v3, v4
	s_cbranch_vccnz .Lmy_xb18_poll
	buffer_wbl2 sc1
	s_waitcnt vmcnt(0)
	v_mov_b32_e32 v3, 1
	global_atomic_add v1, v3, s[98:99]
